# row-sumsq words prefetched at tile header for GEMM1/3 (staged residual epilogue kept)
# speedup vs baseline: 1.0126x; 1.0024x over previous
; __device__ __forceinline__ float rinv_from(u64 v) { return rsqrtf((float)v * (1.0f / 16777216.0f) * (1.0f / 1024.0f) + RMS_EPS); }
;     __host__ __device__ bool next(int i, Unit& u) const {
;         const long L = (long)i * G + c; if (L >= nwg) return false;
;         int wgid = (int)L; { const int q = nwg / NXCD, r = nwg % NXCD, xcd = wgid % NXCD, off = wgid / NXCD; wgid = (xcd < r ? xcd * (q + 1) : r * (q + 1) + (xcd - r) * q) + off; }
;         const int nig = WGM * nN, gid = wgid / nig, fm = gid * WGM, gsz = (nM - fm) < WGM ? (nM - fm) : WGM;
;         u.pm = fm + ((wgid % nig) % gsz); u.pn = (wgid % nig) / gsz; return true;
;     }
;     __device__ __forceinline__ void operator()(const f32x4 (&acc)[2][2][4][2], const Unit& u, int wr, int wc, int fr, int fq) const {
;     ...
;         for (int ai = 0; ai < 2; ++ai) rl[ai] = rinv_from(ssq[u.pm * BM + ai * HALF + wr * 64 + ln]);
.LBB0_106:
	v_lshlrev_b32_e32 v152, 3, v155
	s_lshl_b32 s32, s2, 8
	s_lshl_b32 s32, s32, 3
	s_add_u32 s100, s42, s32
	s_addc_u32 s101, s43, 0
	global_load_dwordx2 v[156:157], v152, s[100:101]
	global_load_dword v159, v152, s[100:101] offset:1024
	global_load_dword v160, v152, s[100:101] offset:1028
	s_add_i32 s84, s84, 1
	s_mul_i32 s4, s84, s87
	s_mul_hi_u32 s5, s84, s95
	s_add_i32 s5, s5, s4
	s_mul_i32 s4, s84, s95
	s_add_u32 s50, s4, s96
	s_addc_u32 s51, s5, s86
	v_mov_b64_e32 v[2:3], 0xa00
	v_cmp_lt_i64_e64 s[36:37], s[50:51], v[2:3]
	v_mov_b64_e32 v[2:3], 0x9ff
	v_cmp_gt_i64_e32 vcc, s[50:51], v[2:3]
	s_cbranch_vccnz .LBB0_108
	s_ashr_i32 s4, s50, 31
	s_lshr_b32 s4, s4, 29
	s_add_i32 s4, s50, s4
	s_ashr_i32 s5, s4, 3
	s_and_b32 s4, s4, -8
	s_sub_i32 s4, s50, s4
	s_cmp_lt_i32 s4, 0
	s_cselect_b32 s6, s10, 0x140
	s_mul_i32 s4, s4, s6
	s_add_i32 s4, s4, s5
	s_mul_hi_i32 s5, s4, 0x66666667
	s_lshr_b32 s6, s5, 31
	s_ashr_i32 s5, s5, 5
	s_add_i32 s5, s5, s6
	s_lshl_b32 s6, s5, 3
	s_sub_i32 s7, 0x100, s6
	s_min_i32 s7, s7, 8
	s_abs_i32 s46, s7
	v_cvt_f32_u32_e32 v2, s46
	s_sub_i32 s48, 0, s46
	s_mulk_i32 s5, 0x50
	s_sub_i32 s4, s4, s5
	v_rcp_iflag_f32_e32 v2, v2
	s_abs_i32 s5, s4
	s_xor_b32 s47, s4, s7
	s_ashr_i32 s47, s47, 31
	v_mul_f32_e32 v2, 0x4f7ffffe, v2
	v_cvt_u32_f32_e32 v2, v2
	s_nop 0
	v_readfirstlane_b32 s49, v2
	s_mul_i32 s48, s48, s49
	s_mul_hi_u32 s48, s49, s48
	s_add_i32 s49, s49, s48
	s_mul_hi_u32 s48, s5, s49
	s_mul_i32 s49, s48, s46
	s_sub_i32 s5, s5, s49
	s_add_i32 s50, s48, 1
	s_sub_i32 s49, s5, s46
	s_cmp_ge_u32 s5, s46
	s_cselect_b32 s48, s50, s48
	s_cselect_b32 s5, s49, s5
	s_add_i32 s49, s48, 1
	s_cmp_ge_u32 s5, s46
	s_cselect_b32 s5, s49, s48
	s_xor_b32 s5, s5, s47
	s_sub_i32 s46, s5, s47
	s_mul_i32 s5, s46, s7
	s_sub_i32 s4, s4, s5
	s_add_i32 s48, s6, s4

; #define LAS __attribute__((address_space(3)))
; __device__ __forceinline__ unsigned cvt_pk_bf16(float lo, float hi) { unsigned r; asm volatile("v_cvt_pk_bf16_f32 %0, %1, %2" : "=v"(r) : "v"(lo), "v"(hi)); return r; }
; __device__ __forceinline__ float rinv_from(u64 v) { return rsqrtf((float)v * (1.0f / 16777216.0f) * (1.0f / 1024.0f) + RMS_EPS); }
;     __device__ __forceinline__ void operator()(const f32x4 (&acc)[2][2][4][2], const Unit& u, int wr, int wc, int fr, int fq) const {
;         const int ln = fr + 16 * fq; const int colw = u.pn * BM + 64 * wc;
;         if (colw >= nvalid) return;
;         float rl[2];
; #pragma unroll
;         for (int ai = 0; ai < 2; ++ai) rl[ai] = rinv_from(ssq[u.pm * BM + ai * HALF + wr * 64 + ln]);
;         LAS unsigned char* sl = stg + (wr * 4 + wc) * EPI_STG_SLICE;
;         const int rr = ln >> 3, cc = ln & 7;
; #pragma unroll
;         for (int ai = 0; ai < 2; ++ai)
; #pragma unroll
;             for (int m = 0; m < 4; ++m) {
;                 const float sc = __shfl(rl[ai], 16 * m + fr);
; #pragma unroll
;                 for (int bj = 0; bj < 2; ++bj) {
;                     f32x4 v0 = acc[ai][bj][m][0] * sc, v1 = acc[ai][bj][m][1] * sc;
;                     if (ACT == 1) {
; #pragma unroll
;                         for (int e = 0; e < 4; ++e) { float a = fmaxf(v0[e], 0.f), b = fmaxf(v1[e], 0.f); v0[e] = a * a; v1[e] = b * b; }
;                     }
;                     u32x4 w; w.x = cvt_pk_bf16(v0[0], v0[1]); w.y = cvt_pk_bf16(v0[2], v0[3]); w.z = cvt_pk_bf16(v1[0], v1[1]); w.w = cvt_pk_bf16(v1[2], v1[3]);
;                     *(LAS u32x4*)(sl + fr * 144 + bj * 64 + fq * 16) = w;
;                 }
;                 const int rowb = u.pm * BM + ai * HALF + wr * 64 + m * 16;
; #pragma unroll
;                 for (int i = 0; i < 2; ++i) { const int r = rr + 8 * i; const u32x4 q = *(const LAS u32x4*)(sl + r * 144 + cc * 16);
;                     __builtin_nontemporal_store(q, (u32x4*)(O + (size_t)(rowb + r) * ldc + colw + cc * 8)); }
.LBB0_114:
	s_lshl_b32 s3, s2, 8
	v_add_u32_e32 v162, s3, v155
	v_ashrrev_i32_e32 v163, 31, v162
	v_lshl_add_u64 v[162:163], v[162:163], 3, s[42:43]
	v_mov_b32_e32 v164, v156
	v_mov_b32_e32 v165, v157
	s_nop 0
	v_mov_b32_e32 v162, v159
	s_mov_b32 s2, 0x33800000
	s_ashr_i32 s27, s26, 31
	s_add_i32 s6, s3, s81
	v_mov_b32_e32 v163, v160
	v_ffbh_u32_e32 v153, v165
	v_min_u32_e32 v153, 32, v153
	v_lshlrev_b64 v[164:165], v153, v[164:165]
	v_min_u32_e32 v161, 1, v164
	v_or_b32_e32 v161, v165, v161
	v_cvt_f32_u32_e32 v161, v161
	v_sub_u32_e32 v153, 32, v153
	v_ldexp_f32 v165, v161, v153
	v_ffbh_u32_e32 v153, v163
	v_min_u32_e32 v153, 32, v153
	v_lshlrev_b64 v[162:163], v153, v[162:163]
	v_min_u32_e32 v161, 1, v162
	v_or_b32_e32 v161, v163, v161
	v_cvt_f32_u32_e32 v161, v161
	v_sub_u32_e32 v153, 32, v153
	v_ldexp_f32 v164, v161, v153
	v_pk_mul_f32 v[162:163], v[164:165], s[2:3] op_sel_hi:[1,0]
	s_mov_b32 s2, 0x3a800000
	v_pk_fma_f32 v[162:163], v[162:163], s[2:3], v[138:139] op_sel_hi:[1,0,0]
	s_add_i32 s2, s3, s77
	v_mul_f32_e32 v153, 0x4b800000, v163
	v_cmp_gt_f32_e64 s[38:39], s70, v163
	v_cmp_gt_f32_e32 vcc, s70, v162
	s_nop 0
	v_cndmask_b32_e64 v153, v163, v153, s[38:39]
	v_rsq_f32_e32 v153, v153
	s_nop 0
	v_mul_f32_e32 v161, 0x45800000, v153
	v_cndmask_b32_e64 v163, v153, v161, s[38:39]
	v_mul_f32_e32 v153, 0x4b800000, v162
	v_cndmask_b32_e32 v153, v162, v153, vcc
	v_rsq_f32_e32 v153, v153
	s_lshl_b64 s[38:39], s[26:27], 1
	v_mul_f32_e32 v161, 0x45800000, v153
	v_cndmask_b32_e32 v161, v153, v161, vcc
	v_and_or_b32 v153, v177, 64, v1
	v_lshlrev_b32_e32 v162, 2, v153
	ds_bpermute_b32 v192, v162, v163
	ds_bpermute_b32 v194, v162, v163 offset:64
	ds_bpermute_b32 v196, v162, v163 offset:128
	ds_bpermute_b32 v198, v162, v163 offset:192
	ds_bpermute_b32 v200, v162, v161
	ds_bpermute_b32 v202, v162, v161 offset:64
	ds_bpermute_b32 v204, v162, v161 offset:128
	ds_bpermute_b32 v206, v162, v161 offset:192
	v_and_b32_e32 v210, 1, v177
	v_and_b32_e32 v211, 14, v177
	v_cmp_eq_u32_e64 s[92:93], 0, v210
	v_mul_u32_u24_e32 v208, 0x1300, v211
	s_mul_i32 s7, s2, 0x1300
	v_lshl_add_u32 v208, v210, 6, v208
	v_bfe_u32 v211, v177, 4, 2
	v_lshl_add_u32 v208, v211, 4, v208
	v_add_u32_e32 v209, 0x1300, v208
	s_add_u32 s62, s40, s7
	s_addc_u32 s63, s41, 0
	s_lshl_b32 s7, s26, 1
	s_add_u32 s62, s62, s7
	s_addc_u32 s63, s63, 0
	s_waitcnt lgkmcnt(7)
	s_mov_b32 s64, s62
	s_mov_b32 s65, s63
	v_pk_mul_f32 v[126:127], v[126:127], v[192:193] op_sel_hi:[1,0]
	v_pk_mul_f32 v[128:129], v[128:129], v[192:193] op_sel_hi:[1,0]
	v_pk_mul_f32 v[122:123], v[122:123], v[192:193] op_sel_hi:[1,0]
	v_pk_mul_f32 v[124:125], v[124:125], v[192:193] op_sel_hi:[1,0]
	v_cvt_pk_bf16_f32 v126, v126, v127
	v_cvt_pk_bf16_f32 v127, v128, v129
	v_cvt_pk_bf16_f32 v128, v122, v123
	v_cvt_pk_bf16_f32 v129, v124, v125
	v_pk_mul_f32 v[118:119], v[118:119], v[192:193] op_sel_hi:[1,0]
	v_pk_mul_f32 v[120:121], v[120:121], v[192:193] op_sel_hi:[1,0]
	v_pk_mul_f32 v[114:115], v[114:115], v[192:193] op_sel_hi:[1,0]
	v_pk_mul_f32 v[116:117], v[116:117], v[192:193] op_sel_hi:[1,0]
	v_cvt_pk_bf16_f32 v118, v118, v119
	v_cvt_pk_bf16_f32 v119, v120, v121
	v_cvt_pk_bf16_f32 v120, v114, v115
	v_cvt_pk_bf16_f32 v121, v116, v117
	v_cndmask_b32_e64 v122, v126, v118, s[92:93]
	v_cndmask_b32_e64 v123, v127, v119, s[92:93]
	v_cndmask_b32_e64 v124, v128, v120, s[92:93]
	v_cndmask_b32_e64 v125, v129, v121, s[92:93]
	v_mov_b32_dpp v114, v122 quad_perm:[1,0,3,2] row_mask:0xf bank_mask:0xf
	v_mov_b32_dpp v115, v123 quad_perm:[1,0,3,2] row_mask:0xf bank_mask:0xf
	v_mov_b32_dpp v116, v124 quad_perm:[1,0,3,2] row_mask:0xf bank_mask:0xf
	v_mov_b32_dpp v117, v125 quad_perm:[1,0,3,2] row_mask:0xf bank_mask:0xf
	v_cndmask_b32_e64 v126, v114, v126, s[92:93]
	v_cndmask_b32_e64 v127, v115, v127, s[92:93]
	v_cndmask_b32_e64 v128, v116, v128, s[92:93]
	v_cndmask_b32_e64 v129, v117, v129, s[92:93]
	v_cndmask_b32_e64 v118, v118, v114, s[92:93]
	v_cndmask_b32_e64 v119, v119, v115, s[92:93]
	v_cndmask_b32_e64 v120, v120, v116, s[92:93]
	v_cndmask_b32_e64 v121, v121, v117, s[92:93]
	global_store_dwordx4 v208, v[126:129], s[64:65] nt
	global_store_dwordx4 v209, v[118:121], s[64:65] nt
	s_waitcnt lgkmcnt(6)
	s_add_u32 s64, s62, 0x13000
	s_addc_u32 s65, s63, 0
	v_pk_mul_f32 v[110:111], v[110:111], v[194:195] op_sel_hi:[1,0]
	v_pk_mul_f32 v[112:113], v[112:113], v[194:195] op_sel_hi:[1,0]
	v_pk_mul_f32 v[106:107], v[106:107], v[194:195] op_sel_hi:[1,0]
	v_pk_mul_f32 v[108:109], v[108:109], v[194:195] op_sel_hi:[1,0]
	v_cvt_pk_bf16_f32 v110, v110, v111
	v_cvt_pk_bf16_f32 v111, v112, v113
	v_cvt_pk_bf16_f32 v112, v106, v107
	v_cvt_pk_bf16_f32 v113, v108, v109
	v_pk_mul_f32 v[102:103], v[102:103], v[194:195] op_sel_hi:[1,0]
	v_pk_mul_f32 v[104:105], v[104:105], v[194:195] op_sel_hi:[1,0]
	v_pk_mul_f32 v[98:99], v[98:99], v[194:195] op_sel_hi:[1,0]
	v_pk_mul_f32 v[100:101], v[100:101], v[194:195] op_sel_hi:[1,0]
	v_cvt_pk_bf16_f32 v102, v102, v103
	v_cvt_pk_bf16_f32 v103, v104, v105
	v_cvt_pk_bf16_f32 v104, v98, v99
	v_cvt_pk_bf16_f32 v105, v100, v101
	v_cndmask_b32_e64 v106, v110, v102, s[92:93]
	v_cndmask_b32_e64 v107, v111, v103, s[92:93]
	v_cndmask_b32_e64 v108, v112, v104, s[92:93]
	v_cndmask_b32_e64 v109, v113, v105, s[92:93]
	v_mov_b32_dpp v98, v106 quad_perm:[1,0,3,2] row_mask:0xf bank_mask:0xf
	v_mov_b32_dpp v99, v107 quad_perm:[1,0,3,2] row_mask:0xf bank_mask:0xf
	v_mov_b32_dpp v100, v108 quad_perm:[1,0,3,2] row_mask:0xf bank_mask:0xf
	v_mov_b32_dpp v101, v109 quad_perm:[1,0,3,2] row_mask:0xf bank_mask:0xf
	v_cndmask_b32_e64 v110, v98, v110, s[92:93]
	v_cndmask_b32_e64 v111, v99, v111, s[92:93]
	v_cndmask_b32_e64 v112, v100, v112, s[92:93]
	v_cndmask_b32_e64 v113, v101, v113, s[92:93]
	v_cndmask_b32_e64 v102, v102, v98, s[92:93]
	v_cndmask_b32_e64 v103, v103, v99, s[92:93]
	v_cndmask_b32_e64 v104, v104, v100, s[92:93]
	v_cndmask_b32_e64 v105, v105, v101, s[92:93]
	global_store_dwordx4 v208, v[110:113], s[64:65] nt
	global_store_dwordx4 v209, v[102:105], s[64:65] nt
	s_waitcnt lgkmcnt(5)
; #define LAS __attribute__((address_space(3)))
; __device__ __forceinline__ unsigned cvt_pk_bf16(float lo, float hi) { unsigned r; asm volatile("v_cvt_pk_bf16_f32 %0, %1, %2" : "=v"(r) : "v"(lo), "v"(hi)); return r; }
;     __device__ __forceinline__ void operator()(const f32x4 (&acc)[2][2][4][2], const Unit& u, int wr, int wc, int fr, int fq) const {
;     ...
;         for (int ai = 0; ai < 2; ++ai)
; #pragma unroll
;             for (int m = 0; m < 4; ++m) {
;                 const float sc = __shfl(rl[ai], 16 * m + fr);
; #pragma unroll
;                 for (int bj = 0; bj < 2; ++bj) {
;                     f32x4 v0 = acc[ai][bj][m][0] * sc, v1 = acc[ai][bj][m][1] * sc;
;                     if (ACT == 1) {
; #pragma unroll
;                         for (int e = 0; e < 4; ++e) { float a = fmaxf(v0[e], 0.f), b = fmaxf(v1[e], 0.f); v0[e] = a * a; v1[e] = b * b; }
;                     }
;                     u32x4 w; w.x = cvt_pk_bf16(v0[0], v0[1]); w.y = cvt_pk_bf16(v0[2], v0[3]); w.z = cvt_pk_bf16(v1[0], v1[1]); w.w = cvt_pk_bf16(v1[2], v1[3]);
;                     *(LAS u32x4*)(sl + fr * 144 + bj * 64 + fq * 16) = w;
;                 }
;                 const int rowb = u.pm * BM + ai * HALF + wr * 64 + m * 16;
; #pragma unroll
;                 for (int i = 0; i < 2; ++i) { const int r = rr + 8 * i; const u32x4 q = *(const LAS u32x4*)(sl + r * 144 + cc * 16);
;                     __builtin_nontemporal_store(q, (u32x4*)(O + (size_t)(rowb + r) * ldc + colw + cc * 8)); }
	s_add_u32 s64, s62, 0x26000
	s_addc_u32 s65, s63, 0
	v_pk_mul_f32 v[94:95], v[94:95], v[196:197] op_sel_hi:[1,0]
	v_pk_mul_f32 v[96:97], v[96:97], v[196:197] op_sel_hi:[1,0]
	v_pk_mul_f32 v[90:91], v[90:91], v[196:197] op_sel_hi:[1,0]
	v_pk_mul_f32 v[92:93], v[92:93], v[196:197] op_sel_hi:[1,0]
	v_cvt_pk_bf16_f32 v94, v94, v95
	v_cvt_pk_bf16_f32 v95, v96, v97
	v_cvt_pk_bf16_f32 v96, v90, v91
	v_cvt_pk_bf16_f32 v97, v92, v93
	v_pk_mul_f32 v[86:87], v[86:87], v[196:197] op_sel_hi:[1,0]
	v_pk_mul_f32 v[88:89], v[88:89], v[196:197] op_sel_hi:[1,0]
	v_pk_mul_f32 v[82:83], v[82:83], v[196:197] op_sel_hi:[1,0]
	v_pk_mul_f32 v[84:85], v[84:85], v[196:197] op_sel_hi:[1,0]
	v_cvt_pk_bf16_f32 v86, v86, v87
	v_cvt_pk_bf16_f32 v87, v88, v89
	v_cvt_pk_bf16_f32 v88, v82, v83
	v_cvt_pk_bf16_f32 v89, v84, v85
	v_cndmask_b32_e64 v90, v94, v86, s[92:93]
	v_cndmask_b32_e64 v91, v95, v87, s[92:93]
	v_cndmask_b32_e64 v92, v96, v88, s[92:93]
	v_cndmask_b32_e64 v93, v97, v89, s[92:93]
	v_mov_b32_dpp v82, v90 quad_perm:[1,0,3,2] row_mask:0xf bank_mask:0xf
	v_mov_b32_dpp v83, v91 quad_perm:[1,0,3,2] row_mask:0xf bank_mask:0xf
	v_mov_b32_dpp v84, v92 quad_perm:[1,0,3,2] row_mask:0xf bank_mask:0xf
	v_mov_b32_dpp v85, v93 quad_perm:[1,0,3,2] row_mask:0xf bank_mask:0xf
	v_cndmask_b32_e64 v94, v82, v94, s[92:93]
	v_cndmask_b32_e64 v95, v83, v95, s[92:93]
	v_cndmask_b32_e64 v96, v84, v96, s[92:93]
	v_cndmask_b32_e64 v97, v85, v97, s[92:93]
	v_cndmask_b32_e64 v86, v86, v82, s[92:93]
	v_cndmask_b32_e64 v87, v87, v83, s[92:93]
	v_cndmask_b32_e64 v88, v88, v84, s[92:93]
	v_cndmask_b32_e64 v89, v89, v85, s[92:93]
	global_store_dwordx4 v208, v[94:97], s[64:65] nt
	global_store_dwordx4 v209, v[86:89], s[64:65] nt
	s_waitcnt lgkmcnt(4)
	s_add_u32 s64, s62, 0x39000
	s_addc_u32 s65, s63, 0
	v_pk_mul_f32 v[78:79], v[78:79], v[198:199] op_sel_hi:[1,0]
	v_pk_mul_f32 v[80:81], v[80:81], v[198:199] op_sel_hi:[1,0]
	v_pk_mul_f32 v[74:75], v[74:75], v[198:199] op_sel_hi:[1,0]
	v_pk_mul_f32 v[76:77], v[76:77], v[198:199] op_sel_hi:[1,0]
	v_cvt_pk_bf16_f32 v78, v78, v79
	v_cvt_pk_bf16_f32 v79, v80, v81
	v_cvt_pk_bf16_f32 v80, v74, v75
	v_cvt_pk_bf16_f32 v81, v76, v77
	v_pk_mul_f32 v[70:71], v[70:71], v[198:199] op_sel_hi:[1,0]
	v_pk_mul_f32 v[72:73], v[72:73], v[198:199] op_sel_hi:[1,0]
	v_pk_mul_f32 v[66:67], v[66:67], v[198:199] op_sel_hi:[1,0]
	v_pk_mul_f32 v[68:69], v[68:69], v[198:199] op_sel_hi:[1,0]
	v_cvt_pk_bf16_f32 v70, v70, v71
	v_cvt_pk_bf16_f32 v71, v72, v73
	v_cvt_pk_bf16_f32 v72, v66, v67
	v_cvt_pk_bf16_f32 v73, v68, v69
	v_cndmask_b32_e64 v74, v78, v70, s[92:93]
	v_cndmask_b32_e64 v75, v79, v71, s[92:93]
	v_cndmask_b32_e64 v76, v80, v72, s[92:93]
	v_cndmask_b32_e64 v77, v81, v73, s[92:93]
	v_mov_b32_dpp v66, v74 quad_perm:[1,0,3,2] row_mask:0xf bank_mask:0xf
	v_mov_b32_dpp v67, v75 quad_perm:[1,0,3,2] row_mask:0xf bank_mask:0xf
	v_mov_b32_dpp v68, v76 quad_perm:[1,0,3,2] row_mask:0xf bank_mask:0xf
	v_mov_b32_dpp v69, v77 quad_perm:[1,0,3,2] row_mask:0xf bank_mask:0xf
	v_cndmask_b32_e64 v78, v66, v78, s[92:93]
	v_cndmask_b32_e64 v79, v67, v79, s[92:93]
	v_cndmask_b32_e64 v80, v68, v80, s[92:93]
	v_cndmask_b32_e64 v81, v69, v81, s[92:93]
	v_cndmask_b32_e64 v70, v70, v66, s[92:93]
	v_cndmask_b32_e64 v71, v71, v67, s[92:93]
	v_cndmask_b32_e64 v72, v72, v68, s[92:93]
	v_cndmask_b32_e64 v73, v73, v69, s[92:93]
	global_store_dwordx4 v208, v[78:81], s[64:65] nt
	global_store_dwordx4 v209, v[70:73], s[64:65] nt
	s_waitcnt lgkmcnt(3)
	s_add_u32 s64, s62, 0x98000
	s_addc_u32 s65, s63, 0
	v_pk_mul_f32 v[62:63], v[62:63], v[200:201] op_sel_hi:[1,0]
	v_pk_mul_f32 v[64:65], v[64:65], v[200:201] op_sel_hi:[1,0]
	v_pk_mul_f32 v[58:59], v[58:59], v[200:201] op_sel_hi:[1,0]
	v_pk_mul_f32 v[60:61], v[60:61], v[200:201] op_sel_hi:[1,0]
	v_cvt_pk_bf16_f32 v62, v62, v63
	v_cvt_pk_bf16_f32 v63, v64, v65
	v_cvt_pk_bf16_f32 v64, v58, v59
	v_cvt_pk_bf16_f32 v65, v60, v61
	v_pk_mul_f32 v[54:55], v[54:55], v[200:201] op_sel_hi:[1,0]
	v_pk_mul_f32 v[56:57], v[56:57], v[200:201] op_sel_hi:[1,0]
	v_pk_mul_f32 v[50:51], v[50:51], v[200:201] op_sel_hi:[1,0]
	v_pk_mul_f32 v[52:53], v[52:53], v[200:201] op_sel_hi:[1,0]
	v_cvt_pk_bf16_f32 v54, v54, v55
	v_cvt_pk_bf16_f32 v55, v56, v57
	v_cvt_pk_bf16_f32 v56, v50, v51
	v_cvt_pk_bf16_f32 v57, v52, v53
	v_cndmask_b32_e64 v58, v62, v54, s[92:93]
	v_cndmask_b32_e64 v59, v63, v55, s[92:93]
	v_cndmask_b32_e64 v60, v64, v56, s[92:93]
	v_cndmask_b32_e64 v61, v65, v57, s[92:93]
	v_mov_b32_dpp v50, v58 quad_perm:[1,0,3,2] row_mask:0xf bank_mask:0xf
	v_mov_b32_dpp v51, v59 quad_perm:[1,0,3,2] row_mask:0xf bank_mask:0xf
	v_mov_b32_dpp v52, v60 quad_perm:[1,0,3,2] row_mask:0xf bank_mask:0xf
	v_mov_b32_dpp v53, v61 quad_perm:[1,0,3,2] row_mask:0xf bank_mask:0xf
	v_cndmask_b32_e64 v62, v50, v62, s[92:93]
	v_cndmask_b32_e64 v63, v51, v63, s[92:93]
	v_cndmask_b32_e64 v64, v52, v64, s[92:93]
	v_cndmask_b32_e64 v65, v53, v65, s[92:93]
	v_cndmask_b32_e64 v54, v54, v50, s[92:93]
	v_cndmask_b32_e64 v55, v55, v51, s[92:93]
	v_cndmask_b32_e64 v56, v56, v52, s[92:93]
	v_cndmask_b32_e64 v57, v57, v53, s[92:93]
	global_store_dwordx4 v208, v[62:65], s[64:65] nt
	global_store_dwordx4 v209, v[54:57], s[64:65] nt
	s_waitcnt lgkmcnt(2)
; #define LAS __attribute__((address_space(3)))
; __device__ __forceinline__ unsigned cvt_pk_bf16(float lo, float hi) { unsigned r; asm volatile("v_cvt_pk_bf16_f32 %0, %1, %2" : "=v"(r) : "v"(lo), "v"(hi)); return r; }
;     __device__ __forceinline__ void operator()(const f32x4 (&acc)[2][2][4][2], const Unit& u, int wr, int wc, int fr, int fq) const {
;     ...
;         for (int ai = 0; ai < 2; ++ai)
; #pragma unroll
;             for (int m = 0; m < 4; ++m) {
;                 const float sc = __shfl(rl[ai], 16 * m + fr);
; #pragma unroll
;                 for (int bj = 0; bj < 2; ++bj) {
;                     f32x4 v0 = acc[ai][bj][m][0] * sc, v1 = acc[ai][bj][m][1] * sc;
;                     if (ACT == 1) {
; #pragma unroll
;                         for (int e = 0; e < 4; ++e) { float a = fmaxf(v0[e], 0.f), b = fmaxf(v1[e], 0.f); v0[e] = a * a; v1[e] = b * b; }
;                     }
;                     u32x4 w; w.x = cvt_pk_bf16(v0[0], v0[1]); w.y = cvt_pk_bf16(v0[2], v0[3]); w.z = cvt_pk_bf16(v1[0], v1[1]); w.w = cvt_pk_bf16(v1[2], v1[3]);
;                     *(LAS u32x4*)(sl + fr * 144 + bj * 64 + fq * 16) = w;
;                 }
;                 const int rowb = u.pm * BM + ai * HALF + wr * 64 + m * 16;
; #pragma unroll
;                 for (int i = 0; i < 2; ++i) { const int r = rr + 8 * i; const u32x4 q = *(const LAS u32x4*)(sl + r * 144 + cc * 16);
;                     __builtin_nontemporal_store(q, (u32x4*)(O + (size_t)(rowb + r) * ldc + colw + cc * 8)); }
; template <class Epi, class Sched, bool ALIGN_EPI = false, bool SP2 = false>
; __device__ __forceinline__ void gemm_phase(LAS unsigned char* lds, const Gemm g, const Sched& S, const Epi& E) {
;     ...
;         if (!has_next) break;
	s_add_u32 s64, s62, 0xab000
	s_addc_u32 s65, s63, 0
	v_pk_mul_f32 v[46:47], v[46:47], v[202:203] op_sel_hi:[1,0]
	v_pk_mul_f32 v[48:49], v[48:49], v[202:203] op_sel_hi:[1,0]
	v_pk_mul_f32 v[42:43], v[42:43], v[202:203] op_sel_hi:[1,0]
	v_pk_mul_f32 v[44:45], v[44:45], v[202:203] op_sel_hi:[1,0]
	v_cvt_pk_bf16_f32 v46, v46, v47
	v_cvt_pk_bf16_f32 v47, v48, v49
	v_cvt_pk_bf16_f32 v48, v42, v43
	v_cvt_pk_bf16_f32 v49, v44, v45
	v_pk_mul_f32 v[38:39], v[38:39], v[202:203] op_sel_hi:[1,0]
	v_pk_mul_f32 v[40:41], v[40:41], v[202:203] op_sel_hi:[1,0]
	v_pk_mul_f32 v[34:35], v[34:35], v[202:203] op_sel_hi:[1,0]
	v_pk_mul_f32 v[36:37], v[36:37], v[202:203] op_sel_hi:[1,0]
	v_cvt_pk_bf16_f32 v38, v38, v39
	v_cvt_pk_bf16_f32 v39, v40, v41
	v_cvt_pk_bf16_f32 v40, v34, v35
	v_cvt_pk_bf16_f32 v41, v36, v37
	v_cndmask_b32_e64 v42, v46, v38, s[92:93]
	v_cndmask_b32_e64 v43, v47, v39, s[92:93]
	v_cndmask_b32_e64 v44, v48, v40, s[92:93]
	v_cndmask_b32_e64 v45, v49, v41, s[92:93]
	v_mov_b32_dpp v34, v42 quad_perm:[1,0,3,2] row_mask:0xf bank_mask:0xf
	v_mov_b32_dpp v35, v43 quad_perm:[1,0,3,2] row_mask:0xf bank_mask:0xf
	v_mov_b32_dpp v36, v44 quad_perm:[1,0,3,2] row_mask:0xf bank_mask:0xf
	v_mov_b32_dpp v37, v45 quad_perm:[1,0,3,2] row_mask:0xf bank_mask:0xf
	v_cndmask_b32_e64 v46, v34, v46, s[92:93]
	v_cndmask_b32_e64 v47, v35, v47, s[92:93]
	v_cndmask_b32_e64 v48, v36, v48, s[92:93]
	v_cndmask_b32_e64 v49, v37, v49, s[92:93]
	v_cndmask_b32_e64 v38, v38, v34, s[92:93]
	v_cndmask_b32_e64 v39, v39, v35, s[92:93]
	v_cndmask_b32_e64 v40, v40, v36, s[92:93]
	v_cndmask_b32_e64 v41, v41, v37, s[92:93]
	global_store_dwordx4 v208, v[46:49], s[64:65] nt
	global_store_dwordx4 v209, v[38:41], s[64:65] nt
	s_waitcnt lgkmcnt(1)
	s_add_u32 s64, s62, 0xbe000
	s_addc_u32 s65, s63, 0
	v_pk_mul_f32 v[30:31], v[30:31], v[204:205] op_sel_hi:[1,0]
	v_pk_mul_f32 v[32:33], v[32:33], v[204:205] op_sel_hi:[1,0]
	v_pk_mul_f32 v[26:27], v[26:27], v[204:205] op_sel_hi:[1,0]
	v_pk_mul_f32 v[28:29], v[28:29], v[204:205] op_sel_hi:[1,0]
	v_cvt_pk_bf16_f32 v30, v30, v31
	v_cvt_pk_bf16_f32 v31, v32, v33
	v_cvt_pk_bf16_f32 v32, v26, v27
	v_cvt_pk_bf16_f32 v33, v28, v29
	v_pk_mul_f32 v[22:23], v[22:23], v[204:205] op_sel_hi:[1,0]
	v_pk_mul_f32 v[24:25], v[24:25], v[204:205] op_sel_hi:[1,0]
	v_pk_mul_f32 v[18:19], v[18:19], v[204:205] op_sel_hi:[1,0]
	v_pk_mul_f32 v[20:21], v[20:21], v[204:205] op_sel_hi:[1,0]
	v_cvt_pk_bf16_f32 v22, v22, v23
	v_cvt_pk_bf16_f32 v23, v24, v25
	v_cvt_pk_bf16_f32 v24, v18, v19
	v_cvt_pk_bf16_f32 v25, v20, v21
	v_cndmask_b32_e64 v26, v30, v22, s[92:93]
	v_cndmask_b32_e64 v27, v31, v23, s[92:93]
	v_cndmask_b32_e64 v28, v32, v24, s[92:93]
	v_cndmask_b32_e64 v29, v33, v25, s[92:93]
	v_mov_b32_dpp v18, v26 quad_perm:[1,0,3,2] row_mask:0xf bank_mask:0xf
	v_mov_b32_dpp v19, v27 quad_perm:[1,0,3,2] row_mask:0xf bank_mask:0xf
	v_mov_b32_dpp v20, v28 quad_perm:[1,0,3,2] row_mask:0xf bank_mask:0xf
	v_mov_b32_dpp v21, v29 quad_perm:[1,0,3,2] row_mask:0xf bank_mask:0xf
	v_cndmask_b32_e64 v30, v18, v30, s[92:93]
	v_cndmask_b32_e64 v31, v19, v31, s[92:93]
	v_cndmask_b32_e64 v32, v20, v32, s[92:93]
	v_cndmask_b32_e64 v33, v21, v33, s[92:93]
	v_cndmask_b32_e64 v22, v22, v18, s[92:93]
	v_cndmask_b32_e64 v23, v23, v19, s[92:93]
	v_cndmask_b32_e64 v24, v24, v20, s[92:93]
	v_cndmask_b32_e64 v25, v25, v21, s[92:93]
	global_store_dwordx4 v208, v[30:33], s[64:65] nt
	global_store_dwordx4 v209, v[22:25], s[64:65] nt
	s_waitcnt lgkmcnt(0)
	s_add_u32 s64, s62, 0xd1000
	s_addc_u32 s65, s63, 0
	v_pk_mul_f32 v[14:15], v[14:15], v[206:207] op_sel_hi:[1,0]
	v_pk_mul_f32 v[16:17], v[16:17], v[206:207] op_sel_hi:[1,0]
	v_pk_mul_f32 v[10:11], v[10:11], v[206:207] op_sel_hi:[1,0]
	v_pk_mul_f32 v[12:13], v[12:13], v[206:207] op_sel_hi:[1,0]
	v_cvt_pk_bf16_f32 v14, v14, v15
	v_cvt_pk_bf16_f32 v15, v16, v17
	v_cvt_pk_bf16_f32 v16, v10, v11
	v_cvt_pk_bf16_f32 v17, v12, v13
	v_pk_mul_f32 v[6:7], v[6:7], v[206:207] op_sel_hi:[1,0]
	v_pk_mul_f32 v[8:9], v[8:9], v[206:207] op_sel_hi:[1,0]
	v_pk_mul_f32 v[2:3], v[2:3], v[206:207] op_sel_hi:[1,0]
	v_pk_mul_f32 v[4:5], v[4:5], v[206:207] op_sel_hi:[1,0]
	v_cvt_pk_bf16_f32 v6, v6, v7
	v_cvt_pk_bf16_f32 v7, v8, v9
	v_cvt_pk_bf16_f32 v8, v2, v3
	v_cvt_pk_bf16_f32 v9, v4, v5
	v_cndmask_b32_e64 v10, v14, v6, s[92:93]
	v_cndmask_b32_e64 v11, v15, v7, s[92:93]
	v_cndmask_b32_e64 v12, v16, v8, s[92:93]
	v_cndmask_b32_e64 v13, v17, v9, s[92:93]
	v_mov_b32_dpp v2, v10 quad_perm:[1,0,3,2] row_mask:0xf bank_mask:0xf
	v_mov_b32_dpp v3, v11 quad_perm:[1,0,3,2] row_mask:0xf bank_mask:0xf
	v_mov_b32_dpp v4, v12 quad_perm:[1,0,3,2] row_mask:0xf bank_mask:0xf
	v_mov_b32_dpp v5, v13 quad_perm:[1,0,3,2] row_mask:0xf bank_mask:0xf
	v_cndmask_b32_e64 v14, v2, v14, s[92:93]
	v_cndmask_b32_e64 v15, v3, v15, s[92:93]
	v_cndmask_b32_e64 v16, v4, v16, s[92:93]
	v_cndmask_b32_e64 v17, v5, v17, s[92:93]
	v_cndmask_b32_e64 v6, v6, v2, s[92:93]
	v_cndmask_b32_e64 v7, v7, v3, s[92:93]
	v_cndmask_b32_e64 v8, v8, v4, s[92:93]
	v_cndmask_b32_e64 v9, v9, v5, s[92:93]
	global_store_dwordx4 v208, v[14:17], s[64:65] nt
	global_store_dwordx4 v209, v[6:9], s[64:65] nt
	s_andn2_b64 vcc, exec, s[36:37]
	s_mov_b64 s[26:27], -1
	s_cbranch_vccnz .LBB0_105

; __device__ __forceinline__ float rinv_from(u64 v) { return rsqrtf((float)v * (1.0f / 16777216.0f) * (1.0f / 1024.0f) + RMS_EPS); }
;     __host__ __device__ bool next(int i, Unit& u) const {
;         const long L = (long)i * G + c; if (L >= nwg) return false;
;         int wgid = (int)L; { const int q = nwg / NXCD, r = nwg % NXCD, xcd = wgid % NXCD, off = wgid / NXCD; wgid = (xcd < r ? xcd * (q + 1) : r * (q + 1) + (xcd - r) * q) + off; }
;         const int nig = WGM * nN, gid = wgid / nig, fm = gid * WGM, gsz = (nM - fm) < WGM ? (nM - fm) : WGM;
;         u.pm = fm + ((wgid % nig) % gsz); u.pn = (wgid % nig) / gsz; return true;
;     }
;     __device__ __forceinline__ void operator()(const f32x4 (&acc)[2][2][4][2], const Unit& u, int wr, int wc, int fr, int fq) const {
;     ...
;         for (int ai = 0; ai < 2; ++ai) rl[ai] = rinv_from(ssq[u.pm * BM + ai * HALF + wr * 64 + ln]);
.LBB0_507:
	v_lshlrev_b32_e32 v152, 3, v155
	s_lshl_b32 s32, s2, 8
	s_add_i32 s32, s32, s79
	s_lshl_b32 s32, s32, 3
	s_add_u32 s100, s28, s32
	s_addc_u32 s101, s29, 0
	global_load_dwordx2 v[156:157], v152, s[100:101]
	global_load_dword v159, v152, s[100:101] offset:1024
	global_load_dword v160, v152, s[100:101] offset:1028
	s_add_i32 s83, s83, 1
	s_mul_i32 s4, s83, s87
	s_mul_hi_u32 s5, s83, s95
	s_add_i32 s5, s5, s4
	s_mul_i32 s4, s83, s95
	s_add_u32 s52, s4, s96
	s_addc_u32 s53, s5, s86
	v_cmp_gt_i64_e32 vcc, s[52:53], v[146:147]
	v_cmp_lt_i64_e64 s[38:39], s[52:53], v[144:145]
	s_cbranch_vccnz .LBB0_513
	s_ashr_i32 s4, s52, 31
	s_lshr_b32 s4, s4, 29
	s_add_i32 s4, s52, s4
	s_and_b32 s5, s4, -8
	s_sub_i32 s5, s52, s5
	s_cmp_gt_i32 s5, -1
	s_mov_b64 s[48:49], -1
	s_cbranch_scc0 .LBB0_510
	s_lshl_b32 s6, s5, 9
	s_mov_b64 s[48:49], 0

; #define LAS __attribute__((address_space(3)))
; __device__ __forceinline__ unsigned cvt_pk_bf16(float lo, float hi) { unsigned r; asm volatile("v_cvt_pk_bf16_f32 %0, %1, %2" : "=v"(r) : "v"(lo), "v"(hi)); return r; }
; __device__ __forceinline__ float rinv_from(u64 v) { return rsqrtf((float)v * (1.0f / 16777216.0f) * (1.0f / 1024.0f) + RMS_EPS); }
;     __device__ __forceinline__ void operator()(const f32x4 (&acc)[2][2][4][2], const Unit& u, int wr, int wc, int fr, int fq) const {
;         const int ln = fr + 16 * fq; const int colw = u.pn * BM + 64 * wc;
;         if (colw >= nvalid) return;
;         float rl[2];
; #pragma unroll
;         for (int ai = 0; ai < 2; ++ai) rl[ai] = rinv_from(ssq[u.pm * BM + ai * HALF + wr * 64 + ln]);
;         LAS unsigned char* sl = stg + (wr * 4 + wc) * EPI_STG_SLICE;
;         const int rr = ln >> 3, cc = ln & 7;
; #pragma unroll
;         for (int ai = 0; ai < 2; ++ai)
; #pragma unroll
;             for (int m = 0; m < 4; ++m) {
;                 const float sc = __shfl(rl[ai], 16 * m + fr);
; #pragma unroll
;                 for (int bj = 0; bj < 2; ++bj) {
;                     f32x4 v0 = acc[ai][bj][m][0] * sc, v1 = acc[ai][bj][m][1] * sc;
;                     if (ACT == 1) {
; #pragma unroll
;                         for (int e = 0; e < 4; ++e) { float a = fmaxf(v0[e], 0.f), b = fmaxf(v1[e], 0.f); v0[e] = a * a; v1[e] = b * b; }
;                     }
;                     u32x4 w; w.x = cvt_pk_bf16(v0[0], v0[1]); w.y = cvt_pk_bf16(v0[2], v0[3]); w.z = cvt_pk_bf16(v1[0], v1[1]); w.w = cvt_pk_bf16(v1[2], v1[3]);
;                     *(LAS u32x4*)(sl + fr * 144 + bj * 64 + fq * 16) = w;
;                 }
;                 const int rowb = u.pm * BM + ai * HALF + wr * 64 + m * 16;
; #pragma unroll
;                 for (int i = 0; i < 2; ++i) { const int r = rr + 8 * i; const u32x4 q = *(const LAS u32x4*)(sl + r * 144 + cc * 16);
;                     __builtin_nontemporal_store(q, (u32x4*)(O + (size_t)(rowb + r) * ldc + colw + cc * 8)); }
.LBB0_519:
	s_lshl_b32 s2, s2, 8
	s_add_i32 s2, s2, s79
	v_or_b32_e32 v162, s2, v155
	v_ashrrev_i32_e32 v163, 31, v162
	v_lshl_add_u64 v[162:163], v[162:163], 3, s[28:29]
	v_mov_b32_e32 v164, v156
	v_mov_b32_e32 v165, v157
	s_nop 0
	v_mov_b32_e32 v162, v159
	s_mov_b32 s4, 0x33800000
	s_ashr_i32 s27, s26, 31
	s_or_b32 s3, s2, 16
	v_mov_b32_e32 v163, v160
	v_ffbh_u32_e32 v153, v165
	v_min_u32_e32 v153, 32, v153
	v_lshlrev_b64 v[164:165], v153, v[164:165]
	v_min_u32_e32 v161, 1, v164
	v_or_b32_e32 v161, v165, v161
	v_cvt_f32_u32_e32 v161, v161
	v_sub_u32_e32 v153, 32, v153
	v_ldexp_f32 v165, v161, v153
	v_ffbh_u32_e32 v153, v163
	v_min_u32_e32 v153, 32, v153
	v_lshlrev_b64 v[162:163], v153, v[162:163]
	v_min_u32_e32 v161, 1, v162
	v_or_b32_e32 v161, v163, v161
	v_cvt_f32_u32_e32 v161, v161
	v_sub_u32_e32 v153, 32, v153
	v_ldexp_f32 v164, v161, v153
	v_pk_mul_f32 v[162:163], v[164:165], s[4:5] op_sel_hi:[1,0]
	s_mov_b32 s4, 0x3a800000
	v_pk_fma_f32 v[162:163], v[162:163], s[4:5], v[138:139] op_sel_hi:[1,0,0]
	s_nop 0
	v_mul_f32_e32 v153, 0x4b800000, v163
	v_cmp_gt_f32_e64 s[40:41], s70, v163
	v_cmp_gt_f32_e32 vcc, s70, v162
	s_nop 0
	v_cndmask_b32_e64 v153, v163, v153, s[40:41]
	v_rsq_f32_e32 v153, v153
	s_nop 0
	v_mul_f32_e32 v161, 0x45800000, v153
	v_cndmask_b32_e64 v163, v153, v161, s[40:41]
	v_mul_f32_e32 v153, 0x4b800000, v162
	v_cndmask_b32_e32 v153, v162, v153, vcc
	v_rsq_f32_e32 v153, v153
	s_lshl_b64 s[40:41], s[26:27], 1
	v_mul_f32_e32 v161, 0x45800000, v153
	v_cndmask_b32_e32 v161, v153, v161, vcc
	v_and_or_b32 v153, v177, 64, v1
	v_lshlrev_b32_e32 v162, 2, v153
	ds_bpermute_b32 v192, v162, v163
	ds_bpermute_b32 v194, v162, v163 offset:64
	ds_bpermute_b32 v196, v162, v163 offset:128
	ds_bpermute_b32 v198, v162, v163 offset:192
	ds_bpermute_b32 v200, v162, v161
	ds_bpermute_b32 v202, v162, v161 offset:64
	ds_bpermute_b32 v204, v162, v161 offset:128
	ds_bpermute_b32 v206, v162, v161 offset:192
	v_and_b32_e32 v210, 1, v177
	v_and_b32_e32 v211, 14, v177
	v_cmp_eq_u32_e64 s[92:93], 0, v210
	v_lshlrev_b32_e32 v208, 13, v211
	s_lshl_b32 s7, s2, 13
	v_lshl_add_u32 v208, v210, 6, v208
	v_bfe_u32 v211, v177, 4, 2
	v_lshl_add_u32 v208, v211, 4, v208
	v_add_u32_e32 v209, 0x2000, v208
	s_add_u32 s62, s44, s7
	s_addc_u32 s63, s45, 0
	s_lshl_b32 s7, s26, 1
	s_add_u32 s62, s62, s7
	s_addc_u32 s63, s63, 0
	s_waitcnt lgkmcnt(7)
	s_mov_b32 s64, s62
	s_mov_b32 s65, s63
	v_pk_mul_f32 v[126:127], v[126:127], v[192:193] op_sel_hi:[1,0]
	v_pk_mul_f32 v[128:129], v[128:129], v[192:193] op_sel_hi:[1,0]
	v_pk_mul_f32 v[122:123], v[122:123], v[192:193] op_sel_hi:[1,0]
	v_pk_mul_f32 v[124:125], v[124:125], v[192:193] op_sel_hi:[1,0]
	v_max_f32_e32 v126, 0, v126
	v_max_f32_e32 v127, 0, v127
	v_max_f32_e32 v128, 0, v128
	v_max_f32_e32 v129, 0, v129
	v_max_f32_e32 v122, 0, v122
	v_max_f32_e32 v123, 0, v123
	v_max_f32_e32 v124, 0, v124
	v_max_f32_e32 v125, 0, v125
	v_pk_mul_f32 v[126:127], v[126:127], v[126:127]
	v_pk_mul_f32 v[128:129], v[128:129], v[128:129]
	v_pk_mul_f32 v[122:123], v[122:123], v[122:123]
	v_pk_mul_f32 v[124:125], v[124:125], v[124:125]
	v_cvt_pk_bf16_f32 v126, v126, v127
	v_cvt_pk_bf16_f32 v127, v128, v129
	v_cvt_pk_bf16_f32 v128, v122, v123
	v_cvt_pk_bf16_f32 v129, v124, v125
	v_pk_mul_f32 v[118:119], v[118:119], v[192:193] op_sel_hi:[1,0]
	v_pk_mul_f32 v[120:121], v[120:121], v[192:193] op_sel_hi:[1,0]
	v_pk_mul_f32 v[114:115], v[114:115], v[192:193] op_sel_hi:[1,0]
	v_pk_mul_f32 v[116:117], v[116:117], v[192:193] op_sel_hi:[1,0]
	v_max_f32_e32 v118, 0, v118
	v_max_f32_e32 v119, 0, v119
	v_max_f32_e32 v120, 0, v120
	v_max_f32_e32 v121, 0, v121
	v_max_f32_e32 v114, 0, v114
	v_max_f32_e32 v115, 0, v115
	v_max_f32_e32 v116, 0, v116
	v_max_f32_e32 v117, 0, v117
	v_pk_mul_f32 v[118:119], v[118:119], v[118:119]
	v_pk_mul_f32 v[120:121], v[120:121], v[120:121]
	v_pk_mul_f32 v[114:115], v[114:115], v[114:115]
	v_pk_mul_f32 v[116:117], v[116:117], v[116:117]
	v_cvt_pk_bf16_f32 v118, v118, v119
	v_cvt_pk_bf16_f32 v119, v120, v121
	v_cvt_pk_bf16_f32 v120, v114, v115
	v_cvt_pk_bf16_f32 v121, v116, v117
	v_cndmask_b32_e64 v122, v126, v118, s[92:93]
	v_cndmask_b32_e64 v123, v127, v119, s[92:93]
	v_cndmask_b32_e64 v124, v128, v120, s[92:93]
	v_cndmask_b32_e64 v125, v129, v121, s[92:93]
	v_mov_b32_dpp v114, v122 quad_perm:[1,0,3,2] row_mask:0xf bank_mask:0xf
	v_mov_b32_dpp v115, v123 quad_perm:[1,0,3,2] row_mask:0xf bank_mask:0xf
	v_mov_b32_dpp v116, v124 quad_perm:[1,0,3,2] row_mask:0xf bank_mask:0xf
	v_mov_b32_dpp v117, v125 quad_perm:[1,0,3,2] row_mask:0xf bank_mask:0xf
	v_cndmask_b32_e64 v126, v114, v126, s[92:93]
	v_cndmask_b32_e64 v127, v115, v127, s[92:93]
	v_cndmask_b32_e64 v128, v116, v128, s[92:93]
	v_cndmask_b32_e64 v129, v117, v129, s[92:93]
	v_cndmask_b32_e64 v118, v118, v114, s[92:93]
	v_cndmask_b32_e64 v119, v119, v115, s[92:93]
	v_cndmask_b32_e64 v120, v120, v116, s[92:93]
	v_cndmask_b32_e64 v121, v121, v117, s[92:93]
	global_store_dwordx4 v208, v[126:129], s[64:65] nt
	global_store_dwordx4 v209, v[118:121], s[64:65] nt
	s_waitcnt lgkmcnt(6)
; #define LAS __attribute__((address_space(3)))
; __device__ __forceinline__ unsigned cvt_pk_bf16(float lo, float hi) { unsigned r; asm volatile("v_cvt_pk_bf16_f32 %0, %1, %2" : "=v"(r) : "v"(lo), "v"(hi)); return r; }
;     __device__ __forceinline__ void operator()(const f32x4 (&acc)[2][2][4][2], const Unit& u, int wr, int wc, int fr, int fq) const {
;     ...
;         for (int ai = 0; ai < 2; ++ai)
; #pragma unroll
;             for (int m = 0; m < 4; ++m) {
;                 const float sc = __shfl(rl[ai], 16 * m + fr);
; #pragma unroll
;                 for (int bj = 0; bj < 2; ++bj) {
;                     f32x4 v0 = acc[ai][bj][m][0] * sc, v1 = acc[ai][bj][m][1] * sc;
;                     if (ACT == 1) {
; #pragma unroll
;                         for (int e = 0; e < 4; ++e) { float a = fmaxf(v0[e], 0.f), b = fmaxf(v1[e], 0.f); v0[e] = a * a; v1[e] = b * b; }
;                     }
;                     u32x4 w; w.x = cvt_pk_bf16(v0[0], v0[1]); w.y = cvt_pk_bf16(v0[2], v0[3]); w.z = cvt_pk_bf16(v1[0], v1[1]); w.w = cvt_pk_bf16(v1[2], v1[3]);
;                     *(LAS u32x4*)(sl + fr * 144 + bj * 64 + fq * 16) = w;
;                 }
;                 const int rowb = u.pm * BM + ai * HALF + wr * 64 + m * 16;
; #pragma unroll
;                 for (int i = 0; i < 2; ++i) { const int r = rr + 8 * i; const u32x4 q = *(const LAS u32x4*)(sl + r * 144 + cc * 16);
;                     __builtin_nontemporal_store(q, (u32x4*)(O + (size_t)(rowb + r) * ldc + colw + cc * 8)); }
	s_add_u32 s64, s62, 0x20000
	s_addc_u32 s65, s63, 0
	v_pk_mul_f32 v[110:111], v[110:111], v[194:195] op_sel_hi:[1,0]
	v_pk_mul_f32 v[112:113], v[112:113], v[194:195] op_sel_hi:[1,0]
	v_pk_mul_f32 v[106:107], v[106:107], v[194:195] op_sel_hi:[1,0]
	v_pk_mul_f32 v[108:109], v[108:109], v[194:195] op_sel_hi:[1,0]
	v_max_f32_e32 v110, 0, v110
	v_max_f32_e32 v111, 0, v111
	v_max_f32_e32 v112, 0, v112
	v_max_f32_e32 v113, 0, v113
	v_max_f32_e32 v106, 0, v106
	v_max_f32_e32 v107, 0, v107
	v_max_f32_e32 v108, 0, v108
	v_max_f32_e32 v109, 0, v109
	v_pk_mul_f32 v[110:111], v[110:111], v[110:111]
	v_pk_mul_f32 v[112:113], v[112:113], v[112:113]
	v_pk_mul_f32 v[106:107], v[106:107], v[106:107]
	v_pk_mul_f32 v[108:109], v[108:109], v[108:109]
	v_cvt_pk_bf16_f32 v110, v110, v111
	v_cvt_pk_bf16_f32 v111, v112, v113
	v_cvt_pk_bf16_f32 v112, v106, v107
	v_cvt_pk_bf16_f32 v113, v108, v109
	v_pk_mul_f32 v[102:103], v[102:103], v[194:195] op_sel_hi:[1,0]
	v_pk_mul_f32 v[104:105], v[104:105], v[194:195] op_sel_hi:[1,0]
	v_pk_mul_f32 v[98:99], v[98:99], v[194:195] op_sel_hi:[1,0]
	v_pk_mul_f32 v[100:101], v[100:101], v[194:195] op_sel_hi:[1,0]
	v_max_f32_e32 v102, 0, v102
	v_max_f32_e32 v103, 0, v103
	v_max_f32_e32 v104, 0, v104
	v_max_f32_e32 v105, 0, v105
	v_max_f32_e32 v98, 0, v98
	v_max_f32_e32 v99, 0, v99
	v_max_f32_e32 v100, 0, v100
	v_max_f32_e32 v101, 0, v101
	v_pk_mul_f32 v[102:103], v[102:103], v[102:103]
	v_pk_mul_f32 v[104:105], v[104:105], v[104:105]
	v_pk_mul_f32 v[98:99], v[98:99], v[98:99]
	v_pk_mul_f32 v[100:101], v[100:101], v[100:101]
	v_cvt_pk_bf16_f32 v102, v102, v103
	v_cvt_pk_bf16_f32 v103, v104, v105
	v_cvt_pk_bf16_f32 v104, v98, v99
	v_cvt_pk_bf16_f32 v105, v100, v101
	v_cndmask_b32_e64 v106, v110, v102, s[92:93]
	v_cndmask_b32_e64 v107, v111, v103, s[92:93]
	v_cndmask_b32_e64 v108, v112, v104, s[92:93]
	v_cndmask_b32_e64 v109, v113, v105, s[92:93]
	v_mov_b32_dpp v98, v106 quad_perm:[1,0,3,2] row_mask:0xf bank_mask:0xf
	v_mov_b32_dpp v99, v107 quad_perm:[1,0,3,2] row_mask:0xf bank_mask:0xf
	v_mov_b32_dpp v100, v108 quad_perm:[1,0,3,2] row_mask:0xf bank_mask:0xf
	v_mov_b32_dpp v101, v109 quad_perm:[1,0,3,2] row_mask:0xf bank_mask:0xf
	v_cndmask_b32_e64 v110, v98, v110, s[92:93]
	v_cndmask_b32_e64 v111, v99, v111, s[92:93]
	v_cndmask_b32_e64 v112, v100, v112, s[92:93]
	v_cndmask_b32_e64 v113, v101, v113, s[92:93]
	v_cndmask_b32_e64 v102, v102, v98, s[92:93]
	v_cndmask_b32_e64 v103, v103, v99, s[92:93]
	v_cndmask_b32_e64 v104, v104, v100, s[92:93]
	v_cndmask_b32_e64 v105, v105, v101, s[92:93]
	global_store_dwordx4 v208, v[110:113], s[64:65] nt
	global_store_dwordx4 v209, v[102:105], s[64:65] nt
	s_waitcnt lgkmcnt(5)
	s_add_u32 s64, s62, 0x40000
	s_addc_u32 s65, s63, 0
	v_pk_mul_f32 v[94:95], v[94:95], v[196:197] op_sel_hi:[1,0]
	v_pk_mul_f32 v[96:97], v[96:97], v[196:197] op_sel_hi:[1,0]
	v_pk_mul_f32 v[90:91], v[90:91], v[196:197] op_sel_hi:[1,0]
	v_pk_mul_f32 v[92:93], v[92:93], v[196:197] op_sel_hi:[1,0]
	v_max_f32_e32 v94, 0, v94
	v_max_f32_e32 v95, 0, v95
	v_max_f32_e32 v96, 0, v96
	v_max_f32_e32 v97, 0, v97
	v_max_f32_e32 v90, 0, v90
	v_max_f32_e32 v91, 0, v91
	v_max_f32_e32 v92, 0, v92
	v_max_f32_e32 v93, 0, v93
	v_pk_mul_f32 v[94:95], v[94:95], v[94:95]
	v_pk_mul_f32 v[96:97], v[96:97], v[96:97]
	v_pk_mul_f32 v[90:91], v[90:91], v[90:91]
	v_pk_mul_f32 v[92:93], v[92:93], v[92:93]
	v_cvt_pk_bf16_f32 v94, v94, v95
	v_cvt_pk_bf16_f32 v95, v96, v97
	v_cvt_pk_bf16_f32 v96, v90, v91
	v_cvt_pk_bf16_f32 v97, v92, v93
	v_pk_mul_f32 v[86:87], v[86:87], v[196:197] op_sel_hi:[1,0]
	v_pk_mul_f32 v[88:89], v[88:89], v[196:197] op_sel_hi:[1,0]
	v_pk_mul_f32 v[82:83], v[82:83], v[196:197] op_sel_hi:[1,0]
	v_pk_mul_f32 v[84:85], v[84:85], v[196:197] op_sel_hi:[1,0]
	v_max_f32_e32 v86, 0, v86
	v_max_f32_e32 v87, 0, v87
	v_max_f32_e32 v88, 0, v88
	v_max_f32_e32 v89, 0, v89
	v_max_f32_e32 v82, 0, v82
	v_max_f32_e32 v83, 0, v83
	v_max_f32_e32 v84, 0, v84
	v_max_f32_e32 v85, 0, v85
	v_pk_mul_f32 v[86:87], v[86:87], v[86:87]
	v_pk_mul_f32 v[88:89], v[88:89], v[88:89]
	v_pk_mul_f32 v[82:83], v[82:83], v[82:83]
	v_pk_mul_f32 v[84:85], v[84:85], v[84:85]
	v_cvt_pk_bf16_f32 v86, v86, v87
	v_cvt_pk_bf16_f32 v87, v88, v89
	v_cvt_pk_bf16_f32 v88, v82, v83
	v_cvt_pk_bf16_f32 v89, v84, v85
	v_cndmask_b32_e64 v90, v94, v86, s[92:93]
	v_cndmask_b32_e64 v91, v95, v87, s[92:93]
	v_cndmask_b32_e64 v92, v96, v88, s[92:93]
	v_cndmask_b32_e64 v93, v97, v89, s[92:93]
	v_mov_b32_dpp v82, v90 quad_perm:[1,0,3,2] row_mask:0xf bank_mask:0xf
	v_mov_b32_dpp v83, v91 quad_perm:[1,0,3,2] row_mask:0xf bank_mask:0xf
	v_mov_b32_dpp v84, v92 quad_perm:[1,0,3,2] row_mask:0xf bank_mask:0xf
	v_mov_b32_dpp v85, v93 quad_perm:[1,0,3,2] row_mask:0xf bank_mask:0xf
	v_cndmask_b32_e64 v94, v82, v94, s[92:93]
	v_cndmask_b32_e64 v95, v83, v95, s[92:93]
	v_cndmask_b32_e64 v96, v84, v96, s[92:93]
	v_cndmask_b32_e64 v97, v85, v97, s[92:93]
	v_cndmask_b32_e64 v86, v86, v82, s[92:93]
	v_cndmask_b32_e64 v87, v87, v83, s[92:93]
	v_cndmask_b32_e64 v88, v88, v84, s[92:93]
	v_cndmask_b32_e64 v89, v89, v85, s[92:93]
	global_store_dwordx4 v208, v[94:97], s[64:65] nt
	global_store_dwordx4 v209, v[86:89], s[64:65] nt
	s_waitcnt lgkmcnt(4)
; #define LAS __attribute__((address_space(3)))
; __device__ __forceinline__ unsigned cvt_pk_bf16(float lo, float hi) { unsigned r; asm volatile("v_cvt_pk_bf16_f32 %0, %1, %2" : "=v"(r) : "v"(lo), "v"(hi)); return r; }
;     __device__ __forceinline__ void operator()(const f32x4 (&acc)[2][2][4][2], const Unit& u, int wr, int wc, int fr, int fq) const {
;     ...
;         for (int ai = 0; ai < 2; ++ai)
; #pragma unroll
;             for (int m = 0; m < 4; ++m) {
;                 const float sc = __shfl(rl[ai], 16 * m + fr);
; #pragma unroll
;                 for (int bj = 0; bj < 2; ++bj) {
;                     f32x4 v0 = acc[ai][bj][m][0] * sc, v1 = acc[ai][bj][m][1] * sc;
;                     if (ACT == 1) {
; #pragma unroll
;                         for (int e = 0; e < 4; ++e) { float a = fmaxf(v0[e], 0.f), b = fmaxf(v1[e], 0.f); v0[e] = a * a; v1[e] = b * b; }
;                     }
;                     u32x4 w; w.x = cvt_pk_bf16(v0[0], v0[1]); w.y = cvt_pk_bf16(v0[2], v0[3]); w.z = cvt_pk_bf16(v1[0], v1[1]); w.w = cvt_pk_bf16(v1[2], v1[3]);
;                     *(LAS u32x4*)(sl + fr * 144 + bj * 64 + fq * 16) = w;
;                 }
;                 const int rowb = u.pm * BM + ai * HALF + wr * 64 + m * 16;
; #pragma unroll
;                 for (int i = 0; i < 2; ++i) { const int r = rr + 8 * i; const u32x4 q = *(const LAS u32x4*)(sl + r * 144 + cc * 16);
;                     __builtin_nontemporal_store(q, (u32x4*)(O + (size_t)(rowb + r) * ldc + colw + cc * 8)); }
	s_add_u32 s64, s62, 0x60000
	s_addc_u32 s65, s63, 0
	v_pk_mul_f32 v[78:79], v[78:79], v[198:199] op_sel_hi:[1,0]
	v_pk_mul_f32 v[80:81], v[80:81], v[198:199] op_sel_hi:[1,0]
	v_pk_mul_f32 v[74:75], v[74:75], v[198:199] op_sel_hi:[1,0]
	v_pk_mul_f32 v[76:77], v[76:77], v[198:199] op_sel_hi:[1,0]
	v_max_f32_e32 v78, 0, v78
	v_max_f32_e32 v79, 0, v79
	v_max_f32_e32 v80, 0, v80
	v_max_f32_e32 v81, 0, v81
	v_max_f32_e32 v74, 0, v74
	v_max_f32_e32 v75, 0, v75
	v_max_f32_e32 v76, 0, v76
	v_max_f32_e32 v77, 0, v77
	v_pk_mul_f32 v[78:79], v[78:79], v[78:79]
	v_pk_mul_f32 v[80:81], v[80:81], v[80:81]
	v_pk_mul_f32 v[74:75], v[74:75], v[74:75]
	v_pk_mul_f32 v[76:77], v[76:77], v[76:77]
	v_cvt_pk_bf16_f32 v78, v78, v79
	v_cvt_pk_bf16_f32 v79, v80, v81
	v_cvt_pk_bf16_f32 v80, v74, v75
	v_cvt_pk_bf16_f32 v81, v76, v77
	v_pk_mul_f32 v[70:71], v[70:71], v[198:199] op_sel_hi:[1,0]
	v_pk_mul_f32 v[72:73], v[72:73], v[198:199] op_sel_hi:[1,0]
	v_pk_mul_f32 v[66:67], v[66:67], v[198:199] op_sel_hi:[1,0]
	v_pk_mul_f32 v[68:69], v[68:69], v[198:199] op_sel_hi:[1,0]
	v_max_f32_e32 v70, 0, v70
	v_max_f32_e32 v71, 0, v71
	v_max_f32_e32 v72, 0, v72
	v_max_f32_e32 v73, 0, v73
	v_max_f32_e32 v66, 0, v66
	v_max_f32_e32 v67, 0, v67
	v_max_f32_e32 v68, 0, v68
	v_max_f32_e32 v69, 0, v69
	v_pk_mul_f32 v[70:71], v[70:71], v[70:71]
	v_pk_mul_f32 v[72:73], v[72:73], v[72:73]
	v_pk_mul_f32 v[66:67], v[66:67], v[66:67]
	v_pk_mul_f32 v[68:69], v[68:69], v[68:69]
	v_cvt_pk_bf16_f32 v70, v70, v71
	v_cvt_pk_bf16_f32 v71, v72, v73
	v_cvt_pk_bf16_f32 v72, v66, v67
	v_cvt_pk_bf16_f32 v73, v68, v69
	v_cndmask_b32_e64 v74, v78, v70, s[92:93]
	v_cndmask_b32_e64 v75, v79, v71, s[92:93]
	v_cndmask_b32_e64 v76, v80, v72, s[92:93]
	v_cndmask_b32_e64 v77, v81, v73, s[92:93]
	v_mov_b32_dpp v66, v74 quad_perm:[1,0,3,2] row_mask:0xf bank_mask:0xf
	v_mov_b32_dpp v67, v75 quad_perm:[1,0,3,2] row_mask:0xf bank_mask:0xf
	v_mov_b32_dpp v68, v76 quad_perm:[1,0,3,2] row_mask:0xf bank_mask:0xf
	v_mov_b32_dpp v69, v77 quad_perm:[1,0,3,2] row_mask:0xf bank_mask:0xf
	v_cndmask_b32_e64 v78, v66, v78, s[92:93]
	v_cndmask_b32_e64 v79, v67, v79, s[92:93]
	v_cndmask_b32_e64 v80, v68, v80, s[92:93]
	v_cndmask_b32_e64 v81, v69, v81, s[92:93]
	v_cndmask_b32_e64 v70, v70, v66, s[92:93]
	v_cndmask_b32_e64 v71, v71, v67, s[92:93]
	v_cndmask_b32_e64 v72, v72, v68, s[92:93]
	v_cndmask_b32_e64 v73, v73, v69, s[92:93]
	global_store_dwordx4 v208, v[78:81], s[64:65] nt
	global_store_dwordx4 v209, v[70:73], s[64:65] nt
	s_waitcnt lgkmcnt(3)
	s_add_u32 s64, s62, 0x100000
	s_addc_u32 s65, s63, 0
	v_pk_mul_f32 v[62:63], v[62:63], v[200:201] op_sel_hi:[1,0]
	v_pk_mul_f32 v[64:65], v[64:65], v[200:201] op_sel_hi:[1,0]
	v_pk_mul_f32 v[58:59], v[58:59], v[200:201] op_sel_hi:[1,0]
	v_pk_mul_f32 v[60:61], v[60:61], v[200:201] op_sel_hi:[1,0]
	v_max_f32_e32 v62, 0, v62
	v_max_f32_e32 v63, 0, v63
	v_max_f32_e32 v64, 0, v64
	v_max_f32_e32 v65, 0, v65
	v_max_f32_e32 v58, 0, v58
	v_max_f32_e32 v59, 0, v59
	v_max_f32_e32 v60, 0, v60
	v_max_f32_e32 v61, 0, v61
	v_pk_mul_f32 v[62:63], v[62:63], v[62:63]
	v_pk_mul_f32 v[64:65], v[64:65], v[64:65]
	v_pk_mul_f32 v[58:59], v[58:59], v[58:59]
	v_pk_mul_f32 v[60:61], v[60:61], v[60:61]
	v_cvt_pk_bf16_f32 v62, v62, v63
	v_cvt_pk_bf16_f32 v63, v64, v65
	v_cvt_pk_bf16_f32 v64, v58, v59
	v_cvt_pk_bf16_f32 v65, v60, v61
	v_pk_mul_f32 v[54:55], v[54:55], v[200:201] op_sel_hi:[1,0]
	v_pk_mul_f32 v[56:57], v[56:57], v[200:201] op_sel_hi:[1,0]
	v_pk_mul_f32 v[50:51], v[50:51], v[200:201] op_sel_hi:[1,0]
	v_pk_mul_f32 v[52:53], v[52:53], v[200:201] op_sel_hi:[1,0]
	v_max_f32_e32 v54, 0, v54
	v_max_f32_e32 v55, 0, v55
	v_max_f32_e32 v56, 0, v56
	v_max_f32_e32 v57, 0, v57
	v_max_f32_e32 v50, 0, v50
	v_max_f32_e32 v51, 0, v51
	v_max_f32_e32 v52, 0, v52
	v_max_f32_e32 v53, 0, v53
	v_pk_mul_f32 v[54:55], v[54:55], v[54:55]
	v_pk_mul_f32 v[56:57], v[56:57], v[56:57]
	v_pk_mul_f32 v[50:51], v[50:51], v[50:51]
	v_pk_mul_f32 v[52:53], v[52:53], v[52:53]
	v_cvt_pk_bf16_f32 v54, v54, v55
	v_cvt_pk_bf16_f32 v55, v56, v57
	v_cvt_pk_bf16_f32 v56, v50, v51
	v_cvt_pk_bf16_f32 v57, v52, v53
	v_cndmask_b32_e64 v58, v62, v54, s[92:93]
	v_cndmask_b32_e64 v59, v63, v55, s[92:93]
	v_cndmask_b32_e64 v60, v64, v56, s[92:93]
	v_cndmask_b32_e64 v61, v65, v57, s[92:93]
	v_mov_b32_dpp v50, v58 quad_perm:[1,0,3,2] row_mask:0xf bank_mask:0xf
	v_mov_b32_dpp v51, v59 quad_perm:[1,0,3,2] row_mask:0xf bank_mask:0xf
	v_mov_b32_dpp v52, v60 quad_perm:[1,0,3,2] row_mask:0xf bank_mask:0xf
	v_mov_b32_dpp v53, v61 quad_perm:[1,0,3,2] row_mask:0xf bank_mask:0xf
	v_cndmask_b32_e64 v62, v50, v62, s[92:93]
	v_cndmask_b32_e64 v63, v51, v63, s[92:93]
	v_cndmask_b32_e64 v64, v52, v64, s[92:93]
	v_cndmask_b32_e64 v65, v53, v65, s[92:93]
	v_cndmask_b32_e64 v54, v54, v50, s[92:93]
	v_cndmask_b32_e64 v55, v55, v51, s[92:93]
	v_cndmask_b32_e64 v56, v56, v52, s[92:93]
	v_cndmask_b32_e64 v57, v57, v53, s[92:93]
	global_store_dwordx4 v208, v[62:65], s[64:65] nt
	global_store_dwordx4 v209, v[54:57], s[64:65] nt
	s_waitcnt lgkmcnt(2)
; #define LAS __attribute__((address_space(3)))
; __device__ __forceinline__ unsigned cvt_pk_bf16(float lo, float hi) { unsigned r; asm volatile("v_cvt_pk_bf16_f32 %0, %1, %2" : "=v"(r) : "v"(lo), "v"(hi)); return r; }
;     __device__ __forceinline__ void operator()(const f32x4 (&acc)[2][2][4][2], const Unit& u, int wr, int wc, int fr, int fq) const {
;     ...
;         for (int ai = 0; ai < 2; ++ai)
; #pragma unroll
;             for (int m = 0; m < 4; ++m) {
;                 const float sc = __shfl(rl[ai], 16 * m + fr);
; #pragma unroll
;                 for (int bj = 0; bj < 2; ++bj) {
;                     f32x4 v0 = acc[ai][bj][m][0] * sc, v1 = acc[ai][bj][m][1] * sc;
;                     if (ACT == 1) {
; #pragma unroll
;                         for (int e = 0; e < 4; ++e) { float a = fmaxf(v0[e], 0.f), b = fmaxf(v1[e], 0.f); v0[e] = a * a; v1[e] = b * b; }
;                     }
;                     u32x4 w; w.x = cvt_pk_bf16(v0[0], v0[1]); w.y = cvt_pk_bf16(v0[2], v0[3]); w.z = cvt_pk_bf16(v1[0], v1[1]); w.w = cvt_pk_bf16(v1[2], v1[3]);
;                     *(LAS u32x4*)(sl + fr * 144 + bj * 64 + fq * 16) = w;
;                 }
;                 const int rowb = u.pm * BM + ai * HALF + wr * 64 + m * 16;
; #pragma unroll
;                 for (int i = 0; i < 2; ++i) { const int r = rr + 8 * i; const u32x4 q = *(const LAS u32x4*)(sl + r * 144 + cc * 16);
;                     __builtin_nontemporal_store(q, (u32x4*)(O + (size_t)(rowb + r) * ldc + colw + cc * 8)); }
	s_add_u32 s64, s62, 0x120000
	s_addc_u32 s65, s63, 0
	v_pk_mul_f32 v[46:47], v[46:47], v[202:203] op_sel_hi:[1,0]
	v_pk_mul_f32 v[48:49], v[48:49], v[202:203] op_sel_hi:[1,0]
	v_pk_mul_f32 v[42:43], v[42:43], v[202:203] op_sel_hi:[1,0]
	v_pk_mul_f32 v[44:45], v[44:45], v[202:203] op_sel_hi:[1,0]
	v_max_f32_e32 v46, 0, v46
	v_max_f32_e32 v47, 0, v47
	v_max_f32_e32 v48, 0, v48
	v_max_f32_e32 v49, 0, v49
	v_max_f32_e32 v42, 0, v42
	v_max_f32_e32 v43, 0, v43
	v_max_f32_e32 v44, 0, v44
	v_max_f32_e32 v45, 0, v45
	v_pk_mul_f32 v[46:47], v[46:47], v[46:47]
	v_pk_mul_f32 v[48:49], v[48:49], v[48:49]
	v_pk_mul_f32 v[42:43], v[42:43], v[42:43]
	v_pk_mul_f32 v[44:45], v[44:45], v[44:45]
	v_cvt_pk_bf16_f32 v46, v46, v47
	v_cvt_pk_bf16_f32 v47, v48, v49
	v_cvt_pk_bf16_f32 v48, v42, v43
	v_cvt_pk_bf16_f32 v49, v44, v45
	v_pk_mul_f32 v[38:39], v[38:39], v[202:203] op_sel_hi:[1,0]
	v_pk_mul_f32 v[40:41], v[40:41], v[202:203] op_sel_hi:[1,0]
	v_pk_mul_f32 v[34:35], v[34:35], v[202:203] op_sel_hi:[1,0]
	v_pk_mul_f32 v[36:37], v[36:37], v[202:203] op_sel_hi:[1,0]
	v_max_f32_e32 v38, 0, v38
	v_max_f32_e32 v39, 0, v39
	v_max_f32_e32 v40, 0, v40
	v_max_f32_e32 v41, 0, v41
	v_max_f32_e32 v34, 0, v34
	v_max_f32_e32 v35, 0, v35
	v_max_f32_e32 v36, 0, v36
	v_max_f32_e32 v37, 0, v37
	v_pk_mul_f32 v[38:39], v[38:39], v[38:39]
	v_pk_mul_f32 v[40:41], v[40:41], v[40:41]
	v_pk_mul_f32 v[34:35], v[34:35], v[34:35]
	v_pk_mul_f32 v[36:37], v[36:37], v[36:37]
	v_cvt_pk_bf16_f32 v38, v38, v39
	v_cvt_pk_bf16_f32 v39, v40, v41
	v_cvt_pk_bf16_f32 v40, v34, v35
	v_cvt_pk_bf16_f32 v41, v36, v37
	v_cndmask_b32_e64 v42, v46, v38, s[92:93]
	v_cndmask_b32_e64 v43, v47, v39, s[92:93]
	v_cndmask_b32_e64 v44, v48, v40, s[92:93]
	v_cndmask_b32_e64 v45, v49, v41, s[92:93]
	v_mov_b32_dpp v34, v42 quad_perm:[1,0,3,2] row_mask:0xf bank_mask:0xf
	v_mov_b32_dpp v35, v43 quad_perm:[1,0,3,2] row_mask:0xf bank_mask:0xf
	v_mov_b32_dpp v36, v44 quad_perm:[1,0,3,2] row_mask:0xf bank_mask:0xf
	v_mov_b32_dpp v37, v45 quad_perm:[1,0,3,2] row_mask:0xf bank_mask:0xf
	v_cndmask_b32_e64 v46, v34, v46, s[92:93]
	v_cndmask_b32_e64 v47, v35, v47, s[92:93]
	v_cndmask_b32_e64 v48, v36, v48, s[92:93]
	v_cndmask_b32_e64 v49, v37, v49, s[92:93]
	v_cndmask_b32_e64 v38, v38, v34, s[92:93]
	v_cndmask_b32_e64 v39, v39, v35, s[92:93]
	v_cndmask_b32_e64 v40, v40, v36, s[92:93]
	v_cndmask_b32_e64 v41, v41, v37, s[92:93]
	global_store_dwordx4 v208, v[46:49], s[64:65] nt
	global_store_dwordx4 v209, v[38:41], s[64:65] nt
	s_waitcnt lgkmcnt(1)
; #define LAS __attribute__((address_space(3)))
; __device__ __forceinline__ unsigned cvt_pk_bf16(float lo, float hi) { unsigned r; asm volatile("v_cvt_pk_bf16_f32 %0, %1, %2" : "=v"(r) : "v"(lo), "v"(hi)); return r; }
;     __device__ __forceinline__ void operator()(const f32x4 (&acc)[2][2][4][2], const Unit& u, int wr, int wc, int fr, int fq) const {
;     ...
;         for (int ai = 0; ai < 2; ++ai)
; #pragma unroll
;             for (int m = 0; m < 4; ++m) {
;                 const float sc = __shfl(rl[ai], 16 * m + fr);
; #pragma unroll
;                 for (int bj = 0; bj < 2; ++bj) {
;                     f32x4 v0 = acc[ai][bj][m][0] * sc, v1 = acc[ai][bj][m][1] * sc;
;                     if (ACT == 1) {
; #pragma unroll
;                         for (int e = 0; e < 4; ++e) { float a = fmaxf(v0[e], 0.f), b = fmaxf(v1[e], 0.f); v0[e] = a * a; v1[e] = b * b; }
;                     }
;                     u32x4 w; w.x = cvt_pk_bf16(v0[0], v0[1]); w.y = cvt_pk_bf16(v0[2], v0[3]); w.z = cvt_pk_bf16(v1[0], v1[1]); w.w = cvt_pk_bf16(v1[2], v1[3]);
;                     *(LAS u32x4*)(sl + fr * 144 + bj * 64 + fq * 16) = w;
;                 }
;                 const int rowb = u.pm * BM + ai * HALF + wr * 64 + m * 16;
; #pragma unroll
;                 for (int i = 0; i < 2; ++i) { const int r = rr + 8 * i; const u32x4 q = *(const LAS u32x4*)(sl + r * 144 + cc * 16);
;                     __builtin_nontemporal_store(q, (u32x4*)(O + (size_t)(rowb + r) * ldc + colw + cc * 8)); }
; template <class Epi, class Sched, bool ALIGN_EPI = false, bool SP2 = false>
; __device__ __forceinline__ void gemm_phase(LAS unsigned char* lds, const Gemm g, const Sched& S, const Epi& E) {
;     ...
;         if (!has_next) break;
	s_add_u32 s64, s62, 0x140000
	s_addc_u32 s65, s63, 0
	v_pk_mul_f32 v[30:31], v[30:31], v[204:205] op_sel_hi:[1,0]
	v_pk_mul_f32 v[32:33], v[32:33], v[204:205] op_sel_hi:[1,0]
	v_pk_mul_f32 v[26:27], v[26:27], v[204:205] op_sel_hi:[1,0]
	v_pk_mul_f32 v[28:29], v[28:29], v[204:205] op_sel_hi:[1,0]
	v_max_f32_e32 v30, 0, v30
	v_max_f32_e32 v31, 0, v31
	v_max_f32_e32 v32, 0, v32
	v_max_f32_e32 v33, 0, v33
	v_max_f32_e32 v26, 0, v26
	v_max_f32_e32 v27, 0, v27
	v_max_f32_e32 v28, 0, v28
	v_max_f32_e32 v29, 0, v29
	v_pk_mul_f32 v[30:31], v[30:31], v[30:31]
	v_pk_mul_f32 v[32:33], v[32:33], v[32:33]
	v_pk_mul_f32 v[26:27], v[26:27], v[26:27]
	v_pk_mul_f32 v[28:29], v[28:29], v[28:29]
	v_cvt_pk_bf16_f32 v30, v30, v31
	v_cvt_pk_bf16_f32 v31, v32, v33
	v_cvt_pk_bf16_f32 v32, v26, v27
	v_cvt_pk_bf16_f32 v33, v28, v29
	v_pk_mul_f32 v[22:23], v[22:23], v[204:205] op_sel_hi:[1,0]
	v_pk_mul_f32 v[24:25], v[24:25], v[204:205] op_sel_hi:[1,0]
	v_pk_mul_f32 v[18:19], v[18:19], v[204:205] op_sel_hi:[1,0]
	v_pk_mul_f32 v[20:21], v[20:21], v[204:205] op_sel_hi:[1,0]
	v_max_f32_e32 v22, 0, v22
	v_max_f32_e32 v23, 0, v23
	v_max_f32_e32 v24, 0, v24
	v_max_f32_e32 v25, 0, v25
	v_max_f32_e32 v18, 0, v18
	v_max_f32_e32 v19, 0, v19
	v_max_f32_e32 v20, 0, v20
	v_max_f32_e32 v21, 0, v21
	v_pk_mul_f32 v[22:23], v[22:23], v[22:23]
	v_pk_mul_f32 v[24:25], v[24:25], v[24:25]
	v_pk_mul_f32 v[18:19], v[18:19], v[18:19]
	v_pk_mul_f32 v[20:21], v[20:21], v[20:21]
	v_cvt_pk_bf16_f32 v22, v22, v23
	v_cvt_pk_bf16_f32 v23, v24, v25
	v_cvt_pk_bf16_f32 v24, v18, v19
	v_cvt_pk_bf16_f32 v25, v20, v21
	v_cndmask_b32_e64 v26, v30, v22, s[92:93]
	v_cndmask_b32_e64 v27, v31, v23, s[92:93]
	v_cndmask_b32_e64 v28, v32, v24, s[92:93]
	v_cndmask_b32_e64 v29, v33, v25, s[92:93]
	v_mov_b32_dpp v18, v26 quad_perm:[1,0,3,2] row_mask:0xf bank_mask:0xf
	v_mov_b32_dpp v19, v27 quad_perm:[1,0,3,2] row_mask:0xf bank_mask:0xf
	v_mov_b32_dpp v20, v28 quad_perm:[1,0,3,2] row_mask:0xf bank_mask:0xf
	v_mov_b32_dpp v21, v29 quad_perm:[1,0,3,2] row_mask:0xf bank_mask:0xf
	v_cndmask_b32_e64 v30, v18, v30, s[92:93]
	v_cndmask_b32_e64 v31, v19, v31, s[92:93]
	v_cndmask_b32_e64 v32, v20, v32, s[92:93]
	v_cndmask_b32_e64 v33, v21, v33, s[92:93]
	v_cndmask_b32_e64 v22, v22, v18, s[92:93]
	v_cndmask_b32_e64 v23, v23, v19, s[92:93]
	v_cndmask_b32_e64 v24, v24, v20, s[92:93]
	v_cndmask_b32_e64 v25, v25, v21, s[92:93]
	global_store_dwordx4 v208, v[30:33], s[64:65] nt
	global_store_dwordx4 v209, v[22:25], s[64:65] nt
	s_waitcnt lgkmcnt(0)
	s_add_u32 s64, s62, 0x160000
	s_addc_u32 s65, s63, 0
	v_pk_mul_f32 v[14:15], v[14:15], v[206:207] op_sel_hi:[1,0]
	v_pk_mul_f32 v[16:17], v[16:17], v[206:207] op_sel_hi:[1,0]
	v_pk_mul_f32 v[10:11], v[10:11], v[206:207] op_sel_hi:[1,0]
	v_pk_mul_f32 v[12:13], v[12:13], v[206:207] op_sel_hi:[1,0]
	v_max_f32_e32 v14, 0, v14
	v_max_f32_e32 v15, 0, v15
	v_max_f32_e32 v16, 0, v16
	v_max_f32_e32 v17, 0, v17
	v_max_f32_e32 v10, 0, v10
	v_max_f32_e32 v11, 0, v11
	v_max_f32_e32 v12, 0, v12
	v_max_f32_e32 v13, 0, v13
	v_pk_mul_f32 v[14:15], v[14:15], v[14:15]
	v_pk_mul_f32 v[16:17], v[16:17], v[16:17]
	v_pk_mul_f32 v[10:11], v[10:11], v[10:11]
	v_pk_mul_f32 v[12:13], v[12:13], v[12:13]
	v_cvt_pk_bf16_f32 v14, v14, v15
	v_cvt_pk_bf16_f32 v15, v16, v17
	v_cvt_pk_bf16_f32 v16, v10, v11
	v_cvt_pk_bf16_f32 v17, v12, v13
	v_pk_mul_f32 v[6:7], v[6:7], v[206:207] op_sel_hi:[1,0]
	v_pk_mul_f32 v[8:9], v[8:9], v[206:207] op_sel_hi:[1,0]
	v_pk_mul_f32 v[2:3], v[2:3], v[206:207] op_sel_hi:[1,0]
	v_pk_mul_f32 v[4:5], v[4:5], v[206:207] op_sel_hi:[1,0]
	v_max_f32_e32 v6, 0, v6
	v_max_f32_e32 v7, 0, v7
	v_max_f32_e32 v8, 0, v8
	v_max_f32_e32 v9, 0, v9
	v_max_f32_e32 v2, 0, v2
	v_max_f32_e32 v3, 0, v3
	v_max_f32_e32 v4, 0, v4
	v_max_f32_e32 v5, 0, v5
	v_pk_mul_f32 v[6:7], v[6:7], v[6:7]
	v_pk_mul_f32 v[8:9], v[8:9], v[8:9]
	v_pk_mul_f32 v[2:3], v[2:3], v[2:3]
	v_pk_mul_f32 v[4:5], v[4:5], v[4:5]
	v_cvt_pk_bf16_f32 v6, v6, v7
	v_cvt_pk_bf16_f32 v7, v8, v9
	v_cvt_pk_bf16_f32 v8, v2, v3
	v_cvt_pk_bf16_f32 v9, v4, v5
	v_cndmask_b32_e64 v10, v14, v6, s[92:93]
	v_cndmask_b32_e64 v11, v15, v7, s[92:93]
	v_cndmask_b32_e64 v12, v16, v8, s[92:93]
	v_cndmask_b32_e64 v13, v17, v9, s[92:93]
	v_mov_b32_dpp v2, v10 quad_perm:[1,0,3,2] row_mask:0xf bank_mask:0xf
	v_mov_b32_dpp v3, v11 quad_perm:[1,0,3,2] row_mask:0xf bank_mask:0xf
	v_mov_b32_dpp v4, v12 quad_perm:[1,0,3,2] row_mask:0xf bank_mask:0xf
	v_mov_b32_dpp v5, v13 quad_perm:[1,0,3,2] row_mask:0xf bank_mask:0xf
	v_cndmask_b32_e64 v14, v2, v14, s[92:93]
	v_cndmask_b32_e64 v15, v3, v15, s[92:93]
	v_cndmask_b32_e64 v16, v4, v16, s[92:93]
	v_cndmask_b32_e64 v17, v5, v17, s[92:93]
	v_cndmask_b32_e64 v6, v6, v2, s[92:93]
	v_cndmask_b32_e64 v7, v7, v3, s[92:93]
	v_cndmask_b32_e64 v8, v8, v4, s[92:93]
	v_cndmask_b32_e64 v9, v9, v5, s[92:93]
	global_store_dwordx4 v208, v[14:17], s[64:65] nt
	global_store_dwordx4 v209, v[6:9], s[64:65] nt
	s_andn2_b64 vcc, exec, s[38:39]
	s_mov_b64 s[26:27], -1
	s_cbranch_vccnz .LBB0_506

; __global__ void __launch_bounds__(512, 2) fwd_kernel(Args args) {
	.amdhsa_kernel _Z10fwd_kernel4Args
		.amdhsa_group_segment_fixed_size 0
		.amdhsa_private_segment_fixed_size 0
		.amdhsa_kernarg_size 432
		.amdhsa_user_sgpr_count 2
		.amdhsa_user_sgpr_dispatch_ptr 0
		.amdhsa_user_sgpr_queue_ptr 0
		.amdhsa_user_sgpr_kernarg_segment_ptr 1
		.amdhsa_user_sgpr_dispatch_id 0
		.amdhsa_user_sgpr_kernarg_preload_length 0
		.amdhsa_user_sgpr_kernarg_preload_offset 0
		.amdhsa_user_sgpr_private_segment_size 0
		.amdhsa_uses_dynamic_stack 0
		.amdhsa_enable_private_segment 0
		.amdhsa_system_sgpr_workgroup_id_x 1
		.amdhsa_system_sgpr_workgroup_id_y 0
		.amdhsa_system_sgpr_workgroup_id_z 0
		.amdhsa_system_sgpr_workgroup_info 0
		.amdhsa_system_vgpr_workitem_id 2
		.amdhsa_next_free_vgpr 256
		.amdhsa_next_free_sgpr 102
		.amdhsa_accum_offset 256
		.amdhsa_reserve_vcc 1
		.amdhsa_float_round_mode_32 0
		.amdhsa_float_round_mode_16_64 0
		.amdhsa_float_denorm_mode_32 3
		.amdhsa_float_denorm_mode_16_64 3
		.amdhsa_dx10_clamp 1
		.amdhsa_ieee_mode 1
		.amdhsa_fp16_overflow 0
		.amdhsa_tg_split 0
		.amdhsa_exception_fp_ieee_invalid_op 0
		.amdhsa_exception_fp_denorm_src 0
		.amdhsa_exception_fp_ieee_div_zero 0
		.amdhsa_exception_fp_ieee_overflow 0
		.amdhsa_exception_fp_ieee_underflow 0
		.amdhsa_exception_fp_ieee_inexact 0
		.amdhsa_exception_int_div_zero 0
	.end_amdhsa_kernel

; __global__ void __launch_bounds__(512, 2) fwd_kernel(Args args) {
amdhsa.kernels:
  - .agpr_count:     0
    .args:
      - .offset:         0
        .size:           176
        .value_kind:     by_value
      - .offset:         176
        .size:           4
        .value_kind:     hidden_block_count_x
      - .offset:         180
        .size:           4
        .value_kind:     hidden_block_count_y
      - .offset:         184
        .size:           4
        .value_kind:     hidden_block_count_z
      - .offset:         188
        .size:           2
        .value_kind:     hidden_group_size_x
      - .offset:         190
        .size:           2
        .value_kind:     hidden_group_size_y
      - .offset:         192
        .size:           2
        .value_kind:     hidden_group_size_z
      - .offset:         194
        .size:           2
        .value_kind:     hidden_remainder_x
      - .offset:         196
        .size:           2
        .value_kind:     hidden_remainder_y
      - .offset:         198
        .size:           2
        .value_kind:     hidden_remainder_z
      - .offset:         216
        .size:           8
        .value_kind:     hidden_global_offset_x
      - .offset:         224
        .size:           8
        .value_kind:     hidden_global_offset_y
      - .offset:         232
        .size:           8
        .value_kind:     hidden_global_offset_z
      - .offset:         240
        .size:           2
        .value_kind:     hidden_grid_dims
      - .offset:         264
        .size:           8
        .value_kind:     hidden_multigrid_sync_arg
      - .offset:         296
        .size:           4
        .value_kind:     hidden_dynamic_lds_size
    .group_segment_fixed_size: 0
    .kernarg_segment_align: 8
    .kernarg_segment_size: 432
    .language:       OpenCL C
    .language_version:
      - 2
      - 0
    .max_flat_workgroup_size: 512
    .name:           _Z10fwd_kernel4Args
    .private_segment_fixed_size: 0
    .sgpr_count:     108
    .sgpr_spill_count: 190
    .symbol:         _Z10fwd_kernel4Args.kd
    .uniform_work_group_size: 1
    .uses_dynamic_stack: false
    .vgpr_count:     256
    .vgpr_spill_count: 0
    .wavefront_size: 64
